# final RMSNorm sweep: four grid-stride iterations per trip with their loads in flight together; invariant g_final slice loaded once
# speedup vs baseline: 1.0038x; 1.0003x over previous
; __global__ void __launch_bounds__(512, 2) fwd_megakernel(Params P) {
;     ...
;     for (int i = blockIdx.x * 512 + threadIdx.x; i < T_TOK * (DM / 4); i += gridDim.x * 512) {
;         const int row = i >> 8, c4 = i & 255;
;         const float rs = rsqrtf(ssq_sum<4>(ssqA + (size_t)row * 4) * (1.0f / DM) + EPS);
;         const u32x2 xv = ((const u32x2*)xb)[i]; const f32x4 gv = ((const f32x4*)P.g_final)[c4];
;         f32x4 v; v[0] = __uint_as_float(xv.x << 16); v[1] = __uint_as_float(xv.x & 0xffff0000u); v[2] = __uint_as_float(xv.y << 16); v[3] = __uint_as_float(xv.y & 0xffff0000u);
;         ((f32x4*)P.out)[i] = v * rs * gv;
;     }
.LBB0_960:
	s_mov_b32 s2, 0x800000
	v_cmp_gt_i32_e32 vcc, s2, v210
	s_and_saveexec_b64 s[0:1], vcc
	v_readlane_b32 s4, v253, 18
	v_readlane_b32 s5, v253, 19
	v_readlane_b32 s6, v253, 20
	v_readlane_b32 s7, v253, 21
	v_readlane_b32 s8, v253, 22
	v_readlane_b32 s9, v253, 23
	v_readlane_b32 s10, v253, 24
	v_readlane_b32 s11, v253, 25
	s_mov_b64 s[4:5], s[8:9]
	s_mov_b64 s[6:7], s[10:11]
	v_readlane_b32 s8, v252, 7
	s_cbranch_execz .LBB0_963
	v_mov_b32_e32 v0, 4
	v_lshlrev_b32_sdwa v0, v0, v208 dst_sel:DWORD dst_unused:UNUSED_PAD src0_sel:DWORD src1_sel:BYTE_0
	v_mov_b32_e32 v1, 0
	v_lshl_add_u64 v[0:1], s[4:5], 0, v[0:1]
	s_mov_b64 s[0:1], 0
	v_mov_b32_e32 v2, 0x358637bd
	s_mov_b32 s3, 0x7fffff
	global_load_dwordx4 v[8:11], v[0:1], off
.Lfin_loop:
	v_add_u32_e32 v32, s8, v210
	v_add_u32_e32 v33, s8, v32
	v_add_u32_e32 v34, s8, v33
	v_ashrrev_i32_e32 v20, 8, v210
	v_ashrrev_i32_e32 v21, 31, v20
	v_mov_b32_e32 v22, v210
	v_ashrrev_i32_e32 v23, 31, v210
	v_lshl_add_u64 v[20:21], v[20:21], 4, s[64:65]
	v_lshl_add_u64 v[24:25], v[22:23], 3, s[66:67]
	global_load_dwordx4 v[40:43], v[20:21], off
	global_load_dwordx2 v[56:57], v[24:25], off
	v_lshl_add_u64 v[64:65], v[22:23], 4, s[6:7]
	v_ashrrev_i32_e32 v20, 8, v32
	v_ashrrev_i32_e32 v21, 31, v20
	v_mov_b32_e32 v22, v32
	v_ashrrev_i32_e32 v23, 31, v32
	v_lshl_add_u64 v[20:21], v[20:21], 4, s[64:65]
	v_lshl_add_u64 v[24:25], v[22:23], 3, s[66:67]
	global_load_dwordx4 v[44:47], v[20:21], off
	global_load_dwordx2 v[58:59], v[24:25], off
	v_lshl_add_u64 v[66:67], v[22:23], 4, s[6:7]
	v_ashrrev_i32_e32 v20, 8, v33
	v_ashrrev_i32_e32 v21, 31, v20
	v_mov_b32_e32 v22, v33
	v_ashrrev_i32_e32 v23, 31, v33
	v_lshl_add_u64 v[20:21], v[20:21], 4, s[64:65]
	v_lshl_add_u64 v[24:25], v[22:23], 3, s[66:67]
	global_load_dwordx4 v[48:51], v[20:21], off
	global_load_dwordx2 v[60:61], v[24:25], off
	v_lshl_add_u64 v[68:69], v[22:23], 4, s[6:7]
	v_ashrrev_i32_e32 v20, 8, v34
	v_ashrrev_i32_e32 v21, 31, v20
	v_mov_b32_e32 v22, v34
	v_ashrrev_i32_e32 v23, 31, v34
	v_lshl_add_u64 v[20:21], v[20:21], 4, s[64:65]
	v_lshl_add_u64 v[24:25], v[22:23], 3, s[66:67]
	global_load_dwordx4 v[52:55], v[20:21], off
	global_load_dwordx2 v[62:63], v[24:25], off
	v_lshl_add_u64 v[70:71], v[22:23], 4, s[6:7]
	v_add_u32_e32 v210, s8, v34
	s_waitcnt vmcnt(0)
	v_mov_b32_e32 v14, v41
	v_mov_b32_e32 v15, v42
	v_mov_b32_e32 v41, v43
	v_pk_add_f32 v[40:41], v[14:15], v[40:41]
	v_lshlrev_b32_e32 v6, 16, v56
	v_add_f32_e32 v3, v40, v41
	v_add_f32_e32 v3, 0, v3
	v_fmamk_f32 v3, v3, 0x3a800000, v2
	v_mul_f32_e32 v4, 0x4b800000, v3
	v_cmp_gt_f32_e32 vcc, s2, v3
	v_and_b32_e32 v7, 0xffff0000, v56
	v_lshlrev_b32_e32 v16, 16, v57
	v_cndmask_b32_e32 v3, v3, v4, vcc
	v_rsq_f32_e32 v3, v3
	v_and_b32_e32 v17, 0xffff0000, v57
	v_mul_f32_e32 v4, 0x45800000, v3
	v_cndmask_b32_e32 v4, v3, v4, vcc
	v_pk_mul_f32 v[14:15], v[4:5], v[6:7] op_sel_hi:[0,1]
	v_pk_mul_f32 v[4:5], v[4:5], v[16:17] op_sel_hi:[0,1]
	v_pk_mul_f32 v[6:7], v[10:11], v[4:5]
	v_pk_mul_f32 v[4:5], v[8:9], v[14:15]
	global_store_dwordx4 v[64:65], v[4:7], off
	v_mov_b32_e32 v14, v45
	v_mov_b32_e32 v15, v46
	v_mov_b32_e32 v45, v47
	v_pk_add_f32 v[44:45], v[14:15], v[44:45]
	v_lshlrev_b32_e32 v6, 16, v58
	v_add_f32_e32 v3, v44, v45
	v_add_f32_e32 v3, 0, v3
	v_fmamk_f32 v3, v3, 0x3a800000, v2
	v_mul_f32_e32 v4, 0x4b800000, v3
	v_cmp_gt_f32_e32 vcc, s2, v3
	v_and_b32_e32 v7, 0xffff0000, v58
	v_lshlrev_b32_e32 v16, 16, v59
	v_cndmask_b32_e32 v3, v3, v4, vcc
	v_rsq_f32_e32 v3, v3
	v_and_b32_e32 v17, 0xffff0000, v59
	v_mul_f32_e32 v4, 0x45800000, v3
	v_cndmask_b32_e32 v4, v3, v4, vcc
	v_pk_mul_f32 v[14:15], v[4:5], v[6:7] op_sel_hi:[0,1]
	v_pk_mul_f32 v[4:5], v[4:5], v[16:17] op_sel_hi:[0,1]
	v_pk_mul_f32 v[6:7], v[10:11], v[4:5]
	v_pk_mul_f32 v[4:5], v[8:9], v[14:15]
	v_cmp_ge_i32_e32 vcc, s3, v32
	s_and_saveexec_b64 s[10:11], vcc
	global_store_dwordx4 v[66:67], v[4:7], off
	s_mov_b64 exec, s[10:11]
	v_mov_b32_e32 v14, v49
	v_mov_b32_e32 v15, v50
	v_mov_b32_e32 v49, v51
	v_pk_add_f32 v[48:49], v[14:15], v[48:49]
	v_lshlrev_b32_e32 v6, 16, v60
	v_add_f32_e32 v3, v48, v49
	v_add_f32_e32 v3, 0, v3
	v_fmamk_f32 v3, v3, 0x3a800000, v2
	v_mul_f32_e32 v4, 0x4b800000, v3
	v_cmp_gt_f32_e32 vcc, s2, v3
	v_and_b32_e32 v7, 0xffff0000, v60
	v_lshlrev_b32_e32 v16, 16, v61
	v_cndmask_b32_e32 v3, v3, v4, vcc
	v_rsq_f32_e32 v3, v3
	v_and_b32_e32 v17, 0xffff0000, v61
	v_mul_f32_e32 v4, 0x45800000, v3
	v_cndmask_b32_e32 v4, v3, v4, vcc
	v_pk_mul_f32 v[14:15], v[4:5], v[6:7] op_sel_hi:[0,1]
	v_pk_mul_f32 v[4:5], v[4:5], v[16:17] op_sel_hi:[0,1]
	v_pk_mul_f32 v[6:7], v[10:11], v[4:5]
	v_pk_mul_f32 v[4:5], v[8:9], v[14:15]
	v_cmp_ge_i32_e32 vcc, s3, v33
	s_and_saveexec_b64 s[10:11], vcc
	global_store_dwordx4 v[68:69], v[4:7], off
	s_mov_b64 exec, s[10:11]
	v_mov_b32_e32 v14, v53
	v_mov_b32_e32 v15, v54
	v_mov_b32_e32 v53, v55
	v_pk_add_f32 v[52:53], v[14:15], v[52:53]
	v_lshlrev_b32_e32 v6, 16, v62
	v_add_f32_e32 v3, v52, v53
	v_add_f32_e32 v3, 0, v3
	v_fmamk_f32 v3, v3, 0x3a800000, v2
	v_mul_f32_e32 v4, 0x4b800000, v3
	v_cmp_gt_f32_e32 vcc, s2, v3
	v_and_b32_e32 v7, 0xffff0000, v62
	v_lshlrev_b32_e32 v16, 16, v63
	v_cndmask_b32_e32 v3, v3, v4, vcc
	v_rsq_f32_e32 v3, v3
	v_and_b32_e32 v17, 0xffff0000, v63
	v_mul_f32_e32 v4, 0x45800000, v3
	v_cndmask_b32_e32 v4, v3, v4, vcc
	v_pk_mul_f32 v[14:15], v[4:5], v[6:7] op_sel_hi:[0,1]
	v_pk_mul_f32 v[4:5], v[4:5], v[16:17] op_sel_hi:[0,1]
	v_pk_mul_f32 v[6:7], v[10:11], v[4:5]
	v_pk_mul_f32 v[4:5], v[8:9], v[14:15]
	v_cmp_ge_i32_e32 vcc, s3, v34
	s_and_saveexec_b64 s[10:11], vcc
	global_store_dwordx4 v[70:71], v[4:7], off
	s_mov_b64 exec, s[10:11]
	v_cmp_lt_i32_e32 vcc, s3, v210
	s_or_b64 s[0:1], vcc, s[0:1]
	s_andn2_b64 exec, exec, s[0:1]
	s_cbranch_execnz .Lfin_loop
